# constant-bias attention tiles with the later code kept at the same 64-byte placement as the st3 version
# baseline (speedup 1.0000x reference)
; #define LDS_BARRIER() asm volatile("s_waitcnt lgkmcnt(0)\n\ts_barrier" ::: "memory")
; #define AT_LOAD(K_, V_, kt) do { const bf16_t* s_ = kvsrc + (size_t)(kt) * 64 * NQKV; K_ = *(const bf16x8*)s_; V_ = *(const bf16x8*)(s_ + 1024); } while (0)
; #define AT_STORE(K_, V_, buf) do { *(LAS bf16x8*)(lds + AT_KOFF + (buf) * 9216 + srow * 144 + sch * 16) = K_; \
;         _Pragma("unroll") for (int j_ = 0; j_ < 8; ++j_) *(LAS short*)(lds + AT_VOFF + (buf) * 9216 + (8 * sch + j_) * 144 + vp * 2) = V_[j_]; } while (0)
; __device__ __forceinline__ void attn_prompt_unit(const Params& P, LAS unsigned char* lds, int li, int b, int h, int g4, const int tid) {
;     ...
;     for (int kt = kt_lo; kt <= kt_hi; kt += 2) {
;         if (kt + 2 <= kt_hi) AT_LOAD(kA, vA, kt + 2);
;         if (kt >= cw - 8 && kt <= cw) attn_tile(lds + AT_KOFF, lds + AT_VOFF, btl + min(cw - kt, 3) * 1024, qr, o, m, l, r32, hi);
;         AT_STORE(kB, vB, 1);
;         LDS_BARRIER();
;         if (kt + 3 <= kt_hi) AT_LOAD(kB, vB, kt + 3);
;         if (kt + 1 >= cw - 8 && kt + 1 <= cw) attn_tile(lds + AT_KOFF + 9216, lds + AT_VOFF + 9216, btl + min(cw - kt - 1, 3) * 1024, qr, o, m, l, r32, hi);
;         if (kt + 2 <= kt_hi) AT_STORE(kA, vA, 0);
;         LDS_BARRIER();
;     }
.LBB0_85:
	s_waitcnt lgkmcnt(0)
	s_barrier
	s_andn2_b64 vcc, exec, s[0:1]
	s_mov_b64 s[0:1], 0xc0000
	s_add_i32 s26, s26, -2
	v_lshl_add_u64 v[106:107], v[106:107], 0, s[0:1]
	s_cbranch_vccz .LBB0_68
	s_mov_b32 s28, s27
	s_branch .LBB0_71
	s_nop 0
	s_nop 0
	s_nop 0
	s_nop 0
	s_nop 0
	s_nop 0
	s_nop 0
	s_nop 0
